# DMA address arithmetic in the three attention tile loops: constant row pitches as shifts instead of 64-bit scalar multiplies
# speedup vs baseline: 1.0034x; 1.0034x over previous
.LBB0_1242:
	s_ff1_i32_b64 s40, s[8:9]
	s_cmp_lg_u64 s[8:9], 0
	s_cselect_b32 s73, s40, -1
	s_cmp_lt_i32 s73, 0
	s_cbranch_scc1 .LBB0_1244
	s_add_i32 s40, s54, -1
	s_and_b32 s40, s40, 3
	s_mulk_i32 s40, 0x6000
	s_add_i32 s50, s40, 0
	s_lshl_b32 vcc_lo, s73, 14
	s_lshl_b32 s40, s73, 12
	s_mov_b32 s41, 0
	s_add_u32 vcc_lo, s95, vcc_lo
	s_addc_u32 vcc_hi, s98, 0
	v_lshl_add_u64 v[2:3], s[40:41], 1, v[150:151]
	s_add_i32 s40, s80, s50
	s_mov_b32 s41, m0
	s_mov_b32 m0, s40
	s_nop 0
	global_load_lds_dwordx4 v[2:3], off
	s_mov_b32 m0, s41
	s_add_i32 s40, s50, 0x2000
	v_lshl_add_u64 v[2:3], v[118:119], 1, vcc
	s_add_i32 s41, s40, s83
	s_mov_b32 s50, m0
	s_mov_b32 m0, s41
	s_nop 0
	global_load_lds_dwordx4 v[2:3], off
	s_mov_b32 m0, s50
	v_lshl_add_u64 v[2:3], v[120:121], 1, vcc
	s_add_i32 s40, s40, s85
	s_mov_b32 s41, m0
	s_mov_b32 m0, s40
	s_nop 0
	global_load_lds_dwordx4 v[2:3], off
	s_mov_b32 m0, s41

.LBB0_1330:
	v_add3_u32 v0, s12, v117, v118
	v_add3_u32 v0, v0, v119, v120
	v_add_u32_e32 v174, v0, v121
	v_add_u32_e32 v175, v0, v122
	ds_read_b64_tr_b16 v[224:225], v174 offset:8192
	ds_read_b64_tr_b16 v[226:227], v174 offset:9216
	ds_read_b64_tr_b16 v[228:229], v175 offset:8192
	ds_read_b64_tr_b16 v[230:231], v175 offset:9216
	ds_read_b64_tr_b16 v[232:233], v174 offset:10240
	ds_read_b64_tr_b16 v[234:235], v174 offset:11264
	ds_read_b64_tr_b16 v[236:237], v175 offset:10240
	ds_read_b64_tr_b16 v[238:239], v175 offset:11264
	s_ff1_i32_b64 s15, s[10:11]
	s_cmp_lg_u64 s[10:11], 0
	s_cselect_b32 s15, s15, -1
	v_max3_f32 v0, v66, v67, v68
	v_max3_f32 v104, v69, v70, v71
	v_max3_f32 v105, v72, v73, v74
	v_max3_f32 v106, v75, v76, v77
	v_max3_f32 v0, v0, v78, v79
	v_max3_f32 v104, v104, v80, v81
	v_max3_f32 v105, v105, v82, v83
	v_max3_f32 v106, v106, v84, v85
	v_max3_f32 v0, v0, v86, v87
	v_max3_f32 v104, v104, v88, v89
	v_max3_f32 v105, v105, v90, v91
	v_max3_f32 v106, v106, v92, v93
	v_max3_f32 v0, v0, v94, v95
	v_max3_f32 v104, v104, v96, v97
	v_max3_f32 v0, v0, v104, v105
	v_max_f32_e32 v104, v0, v106
	v_mov_b32_e32 v105, v104
	s_cmp_lt_i32 s15, 0
	s_nop 0
	v_permlane32_swap_b32 v104, v105
	s_cbranch_scc1 .LBB0_1332
	s_lshl_b32 s16, s15, 13
	s_add_i32 s13, s13, 0xc000
	s_mov_b32 s17, 0
	s_and_b32 s13, s13, 0xc000
	s_add_i32 s13, s13, 0
	v_lshl_add_u64 v[106:107], v[100:101], 0, s[16:17]
	s_add_i32 s13, s92, s13
	s_mov_b32 s19, m0
	s_mov_b32 m0, s13
	s_nop 0
	global_load_lds_dwordx4 v[106:107], off
	s_mov_b32 m0, s19
	v_lshl_add_u64 v[106:107], v[102:103], 0, s[16:17]
	s_addk_i32 s13, 0x2000
	s_mov_b32 s16, m0
	s_mov_b32 m0, s13
	s_nop 0
	global_load_lds_dwordx4 v[106:107], off
	s_mov_b32 m0, s16

.LBB0_1360:
	s_ff1_i32_b64 s10, s[88:89]
	s_cmp_lg_u64 s[88:89], 0
	s_cselect_b32 s12, s10, -1
	s_nop 7
	v_max3_f32 v162, v98, v99, v100
	v_max3_f32 v163, v101, v102, v103
	v_max3_f32 v164, v104, v105, v106
	v_max3_f32 v165, v107, v108, v109
	v_max3_f32 v162, v162, v110, v111
	v_max3_f32 v163, v163, v112, v113
	v_max3_f32 v164, v164, v114, v115
	v_max3_f32 v165, v165, v116, v117
	v_max3_f32 v162, v162, v118, v119
	v_max3_f32 v163, v163, v120, v121
	v_max3_f32 v164, v164, v122, v123
	v_max3_f32 v165, v165, v124, v125
	v_max3_f32 v162, v162, v126, v127
	v_max3_f32 v163, v163, v128, v129
	v_max3_f32 v162, v162, v163, v164
	v_max_f32_e32 v162, v162, v165
	v_mov_b32_e32 v163, v162
	s_cmp_lt_i32 s12, 0
	s_nop 1
	v_permlane32_swap_b32 v162, v163
	s_cbranch_scc1 .LBB0_1362
	s_add_i32 s42, s42, 0xc000
	s_and_b32 s10, s42, 0xc000
	s_add_i32 s13, s10, 0
	s_lshl_b32 s10, s12, 13
	s_mov_b32 s11, 0
	v_lshl_add_u64 v[164:165], v[158:159], 0, s[10:11]
	s_add_i32 s13, s92, s13
	s_mov_b32 s14, m0
	s_mov_b32 m0, s13
	s_nop 0
	global_load_lds_dwordx4 v[164:165], off
	s_mov_b32 m0, s14
	v_lshl_add_u64 v[164:165], v[160:161], 0, s[10:11]
	s_addk_i32 s13, 0x2000
	s_mov_b32 s10, m0
	s_mov_b32 m0, s13
	s_nop 0
	global_load_lds_dwordx4 v[164:165], off
	s_mov_b32 m0, s10
